# SwiGLU epilogue hand-written: packed f32 mul/add, exp/rcp batched per 8 elements, constant-step store addresses
# speedup vs baseline: 1.0083x; 1.0038x over previous
.LBB0_85:
	v_lshl_or_b32 v144, s26, 7, v147
	v_readlane_b32 s26, v252, 5
	v_readlane_b32 s27, v252, 6
	v_lshl_add_u32 v149, s50, 8, v37
	v_ashrrev_i32_e32 v145, 31, v144
	s_movk_i32 s0, 0x1600
	s_mov_b32 vcc_lo, 0xbfb8aa3b
	s_mov_b32 vcc_hi, 0xbfb8aa3b
	v_lshlrev_b64 v[144:145], 1, v[144:145]
	v_mov_b64_e32 v[142:143], s[26:27]
	v_mad_i64_i32 v[150:151], s[26:27], v149, s0, v[142:143]
	v_pk_mul_f32 v[126:127], v[130:131], v[126:127]
	v_pk_mul_f32 v[128:129], v[132:133], v[128:129]
	v_pk_mul_f32 v[118:119], v[122:123], v[118:119]
	v_pk_mul_f32 v[120:121], v[124:125], v[120:121]
	v_pk_mul_f32 v[130:131], v[130:131], vcc op_sel_hi:[1,0]
	v_pk_mul_f32 v[132:133], v[132:133], vcc op_sel_hi:[1,0]
	v_pk_mul_f32 v[122:123], v[122:123], vcc op_sel_hi:[1,0]
	v_pk_mul_f32 v[124:125], v[124:125], vcc op_sel_hi:[1,0]
	v_exp_f32_e32 v130, v130
	v_exp_f32_e32 v131, v131
	v_exp_f32_e32 v132, v132
	v_exp_f32_e32 v133, v133
	v_exp_f32_e32 v122, v122
	v_exp_f32_e32 v123, v123
	v_exp_f32_e32 v124, v124
	v_exp_f32_e32 v125, v125
	v_pk_add_f32 v[130:131], v[130:131], 1.0 op_sel_hi:[1,0]
	v_pk_add_f32 v[132:133], v[132:133], 1.0 op_sel_hi:[1,0]
	v_pk_add_f32 v[122:123], v[122:123], 1.0 op_sel_hi:[1,0]
	v_pk_add_f32 v[124:125], v[124:125], 1.0 op_sel_hi:[1,0]
	v_rcp_f32_e32 v130, v130
	v_rcp_f32_e32 v131, v131
	v_rcp_f32_e32 v132, v132
	v_rcp_f32_e32 v133, v133
	v_rcp_f32_e32 v122, v122
	v_rcp_f32_e32 v123, v123
	v_rcp_f32_e32 v124, v124
	v_rcp_f32_e32 v125, v125
	v_pk_mul_f32 v[126:127], v[126:127], v[130:131]
	v_pk_mul_f32 v[128:129], v[128:129], v[132:133]
	v_pk_mul_f32 v[118:119], v[118:119], v[122:123]
	v_pk_mul_f32 v[120:121], v[120:121], v[124:125]
	v_cvt_pk_bf16_f32 v130, v126, v127
	v_cvt_pk_bf16_f32 v131, v128, v129
	v_cvt_pk_bf16_f32 v132, v118, v119
	v_cvt_pk_bf16_f32 v133, v120, v121
	v_lshl_add_u64 v[150:151], v[150:151], 0, v[144:145]
	global_store_dwordx4 v[150:151], v[130:133], off sc1
	v_pk_mul_f32 v[110:111], v[114:115], v[110:111]
	v_pk_mul_f32 v[112:113], v[116:117], v[112:113]
	v_pk_mul_f32 v[102:103], v[106:107], v[102:103]
	v_pk_mul_f32 v[104:105], v[108:109], v[104:105]
	v_pk_mul_f32 v[114:115], v[114:115], vcc op_sel_hi:[1,0]
	v_pk_mul_f32 v[116:117], v[116:117], vcc op_sel_hi:[1,0]
	v_pk_mul_f32 v[106:107], v[106:107], vcc op_sel_hi:[1,0]
	v_pk_mul_f32 v[108:109], v[108:109], vcc op_sel_hi:[1,0]
	v_exp_f32_e32 v114, v114
	v_exp_f32_e32 v115, v115
	v_exp_f32_e32 v116, v116
	v_exp_f32_e32 v117, v117
	v_exp_f32_e32 v106, v106
	v_exp_f32_e32 v107, v107
	v_exp_f32_e32 v108, v108
	v_exp_f32_e32 v109, v109
	v_pk_add_f32 v[114:115], v[114:115], 1.0 op_sel_hi:[1,0]
	v_pk_add_f32 v[116:117], v[116:117], 1.0 op_sel_hi:[1,0]
	v_pk_add_f32 v[106:107], v[106:107], 1.0 op_sel_hi:[1,0]
	v_pk_add_f32 v[108:109], v[108:109], 1.0 op_sel_hi:[1,0]
	v_rcp_f32_e32 v114, v114
	v_rcp_f32_e32 v115, v115
	v_rcp_f32_e32 v116, v116
	v_rcp_f32_e32 v117, v117
	v_rcp_f32_e32 v106, v106
	v_rcp_f32_e32 v107, v107
	v_rcp_f32_e32 v108, v108
	v_rcp_f32_e32 v109, v109
	v_pk_mul_f32 v[110:111], v[110:111], v[114:115]
	v_pk_mul_f32 v[112:113], v[112:113], v[116:117]
	v_pk_mul_f32 v[102:103], v[102:103], v[106:107]
	v_pk_mul_f32 v[104:105], v[104:105], v[108:109]
	v_cvt_pk_bf16_f32 v114, v110, v111
	v_cvt_pk_bf16_f32 v115, v112, v113
	v_cvt_pk_bf16_f32 v116, v102, v103
	v_cvt_pk_bf16_f32 v117, v104, v105
	s_mov_b32 s26, 0x16000
	s_mov_b32 s27, 0
	v_lshl_add_u64 v[118:119], v[150:151], 0, s[26:27]
	global_store_dwordx4 v[118:119], v[114:117], off sc1
	v_pk_mul_f32 v[94:95], v[98:99], v[94:95]
	v_pk_mul_f32 v[96:97], v[100:101], v[96:97]
	v_pk_mul_f32 v[86:87], v[90:91], v[86:87]
	v_pk_mul_f32 v[88:89], v[92:93], v[88:89]
	v_pk_mul_f32 v[98:99], v[98:99], vcc op_sel_hi:[1,0]
	v_pk_mul_f32 v[100:101], v[100:101], vcc op_sel_hi:[1,0]
	v_pk_mul_f32 v[90:91], v[90:91], vcc op_sel_hi:[1,0]
	v_pk_mul_f32 v[92:93], v[92:93], vcc op_sel_hi:[1,0]
	v_exp_f32_e32 v98, v98
	v_exp_f32_e32 v99, v99
	v_exp_f32_e32 v100, v100
	v_exp_f32_e32 v101, v101
	v_exp_f32_e32 v90, v90
	v_exp_f32_e32 v91, v91
	v_exp_f32_e32 v92, v92
	v_exp_f32_e32 v93, v93
	v_pk_add_f32 v[98:99], v[98:99], 1.0 op_sel_hi:[1,0]
	v_pk_add_f32 v[100:101], v[100:101], 1.0 op_sel_hi:[1,0]
	v_pk_add_f32 v[90:91], v[90:91], 1.0 op_sel_hi:[1,0]
	v_pk_add_f32 v[92:93], v[92:93], 1.0 op_sel_hi:[1,0]
	v_rcp_f32_e32 v98, v98
	v_rcp_f32_e32 v99, v99
	v_rcp_f32_e32 v100, v100
	v_rcp_f32_e32 v101, v101
	v_rcp_f32_e32 v90, v90
	v_rcp_f32_e32 v91, v91
	v_rcp_f32_e32 v92, v92
	v_rcp_f32_e32 v93, v93
	v_pk_mul_f32 v[94:95], v[94:95], v[98:99]
	v_pk_mul_f32 v[96:97], v[96:97], v[100:101]
	v_pk_mul_f32 v[86:87], v[86:87], v[90:91]
	v_pk_mul_f32 v[88:89], v[88:89], v[92:93]
	v_cvt_pk_bf16_f32 v98, v94, v95
	v_cvt_pk_bf16_f32 v99, v96, v97
	v_cvt_pk_bf16_f32 v100, v86, v87
	v_cvt_pk_bf16_f32 v101, v88, v89
	s_mov_b32 s26, 0x2c000
	s_mov_b32 s27, 0
	v_lshl_add_u64 v[102:103], v[150:151], 0, s[26:27]
	global_store_dwordx4 v[102:103], v[98:101], off sc1
	v_pk_mul_f32 v[78:79], v[82:83], v[78:79]
	v_pk_mul_f32 v[80:81], v[84:85], v[80:81]
	v_pk_mul_f32 v[70:71], v[74:75], v[70:71]
	v_pk_mul_f32 v[72:73], v[76:77], v[72:73]
	v_pk_mul_f32 v[82:83], v[82:83], vcc op_sel_hi:[1,0]
	v_pk_mul_f32 v[84:85], v[84:85], vcc op_sel_hi:[1,0]
	v_pk_mul_f32 v[74:75], v[74:75], vcc op_sel_hi:[1,0]
	v_pk_mul_f32 v[76:77], v[76:77], vcc op_sel_hi:[1,0]
	v_exp_f32_e32 v82, v82
	v_exp_f32_e32 v83, v83
	v_exp_f32_e32 v84, v84
	v_exp_f32_e32 v85, v85
	v_exp_f32_e32 v74, v74
	v_exp_f32_e32 v75, v75
	v_exp_f32_e32 v76, v76
	v_exp_f32_e32 v77, v77
	v_pk_add_f32 v[82:83], v[82:83], 1.0 op_sel_hi:[1,0]
	v_pk_add_f32 v[84:85], v[84:85], 1.0 op_sel_hi:[1,0]
	v_pk_add_f32 v[74:75], v[74:75], 1.0 op_sel_hi:[1,0]
	v_pk_add_f32 v[76:77], v[76:77], 1.0 op_sel_hi:[1,0]
	v_rcp_f32_e32 v82, v82
	v_rcp_f32_e32 v83, v83
	v_rcp_f32_e32 v84, v84
	v_rcp_f32_e32 v85, v85
	v_rcp_f32_e32 v74, v74
	v_rcp_f32_e32 v75, v75
	v_rcp_f32_e32 v76, v76
	v_rcp_f32_e32 v77, v77
	v_pk_mul_f32 v[78:79], v[78:79], v[82:83]
	v_pk_mul_f32 v[80:81], v[80:81], v[84:85]
	v_pk_mul_f32 v[70:71], v[70:71], v[74:75]
	v_pk_mul_f32 v[72:73], v[72:73], v[76:77]
	v_cvt_pk_bf16_f32 v82, v78, v79
	v_cvt_pk_bf16_f32 v83, v80, v81
	v_cvt_pk_bf16_f32 v84, v70, v71
	v_cvt_pk_bf16_f32 v85, v72, v73
	s_mov_b32 s26, 0x42000
	s_mov_b32 s27, 0
	v_lshl_add_u64 v[86:87], v[150:151], 0, s[26:27]
	global_store_dwordx4 v[86:87], v[82:85], off sc1
	v_pk_mul_f32 v[62:63], v[66:67], v[62:63]
	v_pk_mul_f32 v[64:65], v[68:69], v[64:65]
	v_pk_mul_f32 v[54:55], v[58:59], v[54:55]
	v_pk_mul_f32 v[56:57], v[60:61], v[56:57]
	v_pk_mul_f32 v[66:67], v[66:67], vcc op_sel_hi:[1,0]
	v_pk_mul_f32 v[68:69], v[68:69], vcc op_sel_hi:[1,0]
	v_pk_mul_f32 v[58:59], v[58:59], vcc op_sel_hi:[1,0]
	v_pk_mul_f32 v[60:61], v[60:61], vcc op_sel_hi:[1,0]
	v_exp_f32_e32 v66, v66
	v_exp_f32_e32 v67, v67
	v_exp_f32_e32 v68, v68
	v_exp_f32_e32 v69, v69
	v_exp_f32_e32 v58, v58
	v_exp_f32_e32 v59, v59
	v_exp_f32_e32 v60, v60
	v_exp_f32_e32 v61, v61
	v_pk_add_f32 v[66:67], v[66:67], 1.0 op_sel_hi:[1,0]
	v_pk_add_f32 v[68:69], v[68:69], 1.0 op_sel_hi:[1,0]
	v_pk_add_f32 v[58:59], v[58:59], 1.0 op_sel_hi:[1,0]
	v_pk_add_f32 v[60:61], v[60:61], 1.0 op_sel_hi:[1,0]
	v_rcp_f32_e32 v66, v66
	v_rcp_f32_e32 v67, v67
	v_rcp_f32_e32 v68, v68
	v_rcp_f32_e32 v69, v69
	v_rcp_f32_e32 v58, v58
	v_rcp_f32_e32 v59, v59
	v_rcp_f32_e32 v60, v60
	v_rcp_f32_e32 v61, v61
	v_pk_mul_f32 v[62:63], v[62:63], v[66:67]
	v_pk_mul_f32 v[64:65], v[64:65], v[68:69]
	v_pk_mul_f32 v[54:55], v[54:55], v[58:59]
	v_pk_mul_f32 v[56:57], v[56:57], v[60:61]
	v_cvt_pk_bf16_f32 v66, v62, v63
	v_cvt_pk_bf16_f32 v67, v64, v65
	v_cvt_pk_bf16_f32 v68, v54, v55
	v_cvt_pk_bf16_f32 v69, v56, v57
	s_mov_b32 s26, 0xb0000
	s_mov_b32 s27, 0
	v_lshl_add_u64 v[70:71], v[150:151], 0, s[26:27]
	global_store_dwordx4 v[70:71], v[66:69], off sc1
	v_pk_mul_f32 v[46:47], v[50:51], v[46:47]
	v_pk_mul_f32 v[48:49], v[52:53], v[48:49]
	v_pk_mul_f32 v[38:39], v[42:43], v[38:39]
	v_pk_mul_f32 v[40:41], v[44:45], v[40:41]
	v_pk_mul_f32 v[50:51], v[50:51], vcc op_sel_hi:[1,0]
	v_pk_mul_f32 v[52:53], v[52:53], vcc op_sel_hi:[1,0]
	v_pk_mul_f32 v[42:43], v[42:43], vcc op_sel_hi:[1,0]
	v_pk_mul_f32 v[44:45], v[44:45], vcc op_sel_hi:[1,0]
	v_exp_f32_e32 v50, v50
	v_exp_f32_e32 v51, v51
	v_exp_f32_e32 v52, v52
	v_exp_f32_e32 v53, v53
	v_exp_f32_e32 v42, v42
	v_exp_f32_e32 v43, v43
	v_exp_f32_e32 v44, v44
	v_exp_f32_e32 v45, v45
	v_pk_add_f32 v[50:51], v[50:51], 1.0 op_sel_hi:[1,0]
	v_pk_add_f32 v[52:53], v[52:53], 1.0 op_sel_hi:[1,0]
	v_pk_add_f32 v[42:43], v[42:43], 1.0 op_sel_hi:[1,0]
	v_pk_add_f32 v[44:45], v[44:45], 1.0 op_sel_hi:[1,0]
	v_rcp_f32_e32 v50, v50
	v_rcp_f32_e32 v51, v51
	v_rcp_f32_e32 v52, v52
	v_rcp_f32_e32 v53, v53
	v_rcp_f32_e32 v42, v42
	v_rcp_f32_e32 v43, v43
	v_rcp_f32_e32 v44, v44
	v_rcp_f32_e32 v45, v45
	v_pk_mul_f32 v[46:47], v[46:47], v[50:51]
	v_pk_mul_f32 v[48:49], v[48:49], v[52:53]
	v_pk_mul_f32 v[38:39], v[38:39], v[42:43]
	v_pk_mul_f32 v[40:41], v[40:41], v[44:45]
	v_cvt_pk_bf16_f32 v50, v46, v47
	v_cvt_pk_bf16_f32 v51, v48, v49
	v_cvt_pk_bf16_f32 v52, v38, v39
	v_cvt_pk_bf16_f32 v53, v40, v41
	s_mov_b32 s26, 0xc6000
	s_mov_b32 s27, 0
	v_lshl_add_u64 v[54:55], v[150:151], 0, s[26:27]
	global_store_dwordx4 v[54:55], v[50:53], off sc1
	v_pk_mul_f32 v[24:25], v[28:29], v[24:25]
	v_pk_mul_f32 v[26:27], v[30:31], v[26:27]
	v_pk_mul_f32 v[16:17], v[20:21], v[16:17]
	v_pk_mul_f32 v[18:19], v[22:23], v[18:19]
	v_pk_mul_f32 v[28:29], v[28:29], vcc op_sel_hi:[1,0]
	v_pk_mul_f32 v[30:31], v[30:31], vcc op_sel_hi:[1,0]
	v_pk_mul_f32 v[20:21], v[20:21], vcc op_sel_hi:[1,0]
	v_pk_mul_f32 v[22:23], v[22:23], vcc op_sel_hi:[1,0]
	v_exp_f32_e32 v28, v28
	v_exp_f32_e32 v29, v29
	v_exp_f32_e32 v30, v30
	v_exp_f32_e32 v31, v31
	v_exp_f32_e32 v20, v20
	v_exp_f32_e32 v21, v21
	v_exp_f32_e32 v22, v22
	v_exp_f32_e32 v23, v23
	v_pk_add_f32 v[28:29], v[28:29], 1.0 op_sel_hi:[1,0]
	v_pk_add_f32 v[30:31], v[30:31], 1.0 op_sel_hi:[1,0]
	v_pk_add_f32 v[20:21], v[20:21], 1.0 op_sel_hi:[1,0]
	v_pk_add_f32 v[22:23], v[22:23], 1.0 op_sel_hi:[1,0]
	v_rcp_f32_e32 v28, v28
	v_rcp_f32_e32 v29, v29
	v_rcp_f32_e32 v30, v30
	v_rcp_f32_e32 v31, v31
	v_rcp_f32_e32 v20, v20
	v_rcp_f32_e32 v21, v21
	v_rcp_f32_e32 v22, v22
	v_rcp_f32_e32 v23, v23
	v_pk_mul_f32 v[24:25], v[24:25], v[28:29]
	v_pk_mul_f32 v[26:27], v[26:27], v[30:31]
	v_pk_mul_f32 v[16:17], v[16:17], v[20:21]
	v_pk_mul_f32 v[18:19], v[18:19], v[22:23]
	v_cvt_pk_bf16_f32 v28, v24, v25
	v_cvt_pk_bf16_f32 v29, v26, v27
	v_cvt_pk_bf16_f32 v30, v16, v17
	v_cvt_pk_bf16_f32 v31, v18, v19
	s_mov_b32 s26, 0xdc000
	s_mov_b32 s27, 0
	v_lshl_add_u64 v[38:39], v[150:151], 0, s[26:27]
	global_store_dwordx4 v[38:39], v[28:31], off sc1
	v_pk_mul_f32 v[8:9], v[12:13], v[8:9]
	v_pk_mul_f32 v[10:11], v[14:15], v[10:11]
	v_pk_mul_f32 v[0:1], v[4:5], v[0:1]
	v_pk_mul_f32 v[2:3], v[6:7], v[2:3]
	v_pk_mul_f32 v[12:13], v[12:13], vcc op_sel_hi:[1,0]
	v_pk_mul_f32 v[14:15], v[14:15], vcc op_sel_hi:[1,0]
	v_pk_mul_f32 v[4:5], v[4:5], vcc op_sel_hi:[1,0]
	v_pk_mul_f32 v[6:7], v[6:7], vcc op_sel_hi:[1,0]
	v_exp_f32_e32 v12, v12
	v_exp_f32_e32 v13, v13
	v_exp_f32_e32 v14, v14
	v_exp_f32_e32 v15, v15
	v_exp_f32_e32 v4, v4
	v_exp_f32_e32 v5, v5
	v_exp_f32_e32 v6, v6
	v_exp_f32_e32 v7, v7
	v_pk_add_f32 v[12:13], v[12:13], 1.0 op_sel_hi:[1,0]
	v_pk_add_f32 v[14:15], v[14:15], 1.0 op_sel_hi:[1,0]
	v_pk_add_f32 v[4:5], v[4:5], 1.0 op_sel_hi:[1,0]
	v_pk_add_f32 v[6:7], v[6:7], 1.0 op_sel_hi:[1,0]
	v_rcp_f32_e32 v12, v12
	v_rcp_f32_e32 v13, v13
	v_rcp_f32_e32 v14, v14
	v_rcp_f32_e32 v15, v15
	v_rcp_f32_e32 v4, v4
	v_rcp_f32_e32 v5, v5
	v_rcp_f32_e32 v6, v6
	v_rcp_f32_e32 v7, v7
	v_pk_mul_f32 v[8:9], v[8:9], v[12:13]
	v_pk_mul_f32 v[10:11], v[10:11], v[14:15]
	v_pk_mul_f32 v[0:1], v[0:1], v[4:5]
	v_pk_mul_f32 v[2:3], v[2:3], v[6:7]
	v_cvt_pk_bf16_f32 v12, v8, v9
	v_cvt_pk_bf16_f32 v13, v10, v11
	v_cvt_pk_bf16_f32 v14, v0, v1
	v_cvt_pk_bf16_f32 v15, v2, v3
	s_mov_b32 s26, 0xf2000
	s_mov_b32 s27, 0
	v_lshl_add_u64 v[16:17], v[150:151], 0, s[26:27]
	global_store_dwordx4 v[16:17], v[12:15], off sc1
	s_cmp_lt_i32 s50, 64
	s_cbranch_scc1 .LBB0_90
	s_waitcnt vmcnt(0)
	s_waitcnt vmcnt(0)
	s_waitcnt vmcnt(0)
	s_mov_b64 s[26:27], exec
	v_readlane_b32 s30, v254, 34
	v_readlane_b32 s31, v254, 35
	s_and_b64 s[30:31], s[26:27], s[30:31]
	s_mov_b64 exec, s[30:31]
	s_cbranch_execz .LBB0_89
	s_mov_b64 s[34:35], exec
	v_mbcnt_lo_u32_b32 v0, s34, 0
	v_mbcnt_hi_u32_b32 v0, s35, v0
	v_cmp_eq_u32_e32 vcc, 0, v0
	s_and_b64 s[30:31], exec, vcc
	s_mov_b64 exec, s[30:31]
	s_cbranch_execz .LBB0_89
	s_lshl_b32 s0, s50, 6
	s_lshl_b64 s[30:31], s[0:1], 2
	v_readlane_b32 s0, v255, 9
	s_add_u32 s0, s0, s30
	v_readlane_b32 s30, v255, 11
	s_addc_u32 s31, s30, s31
	s_add_u32 s30, s0, 0xffffc000
	s_addc_u32 s31, s31, -1
	s_bcnt1_i32_b64 s0, s[34:35]
	v_mov_b32_e32 v0, s0
	global_atomic_add v33, v0, s[30:31]
